# static s_setprio 1 for waves 0-3 (the leading half) across the sample attention loop, per-iteration priority flips removed
# baseline (speedup 1.0000x reference)
.LBB0_374:
	s_andn2_saveexec_b64 s[0:1], s[0:1]
	v_lshlrev_b64 v[0:1], 10, v[2:3]
	v_lshl_add_u64 v[0:1], s[2:3], 0, v[0:1]
	v_mov_b32_e32 v13, v137
	v_lshl_add_u64 v[0:1], v[0:1], 0, v[12:13]
	s_or_b64 exec, exec, s[0:1]
	s_ashr_i32 s71, s70, 31
	s_lshl_b64 s[0:1], s[70:71], 1
	v_readlane_b32 s4, v252, 63
	v_readlane_b32 s5, v253, 0
	s_add_u32 s0, s4, s0
	s_addc_u32 s1, s5, s1
	v_mov_b32_e32 v15, v137
	global_load_dwordx4 v[104:107], v[0:1], off
	v_lshl_add_u64 v[0:1], s[0:1], 0, v[14:15]
	v_lshl_add_u64 v[2:3], v[0:1], 0, v[136:137]
	v_mov_b32_e32 v121, v137
	v_lshl_add_u64 v[0:1], v[0:1], 0, v[120:121]
	global_load_dwordx4 v[108:111], v[2:3], off
	global_load_dwordx4 v[112:115], v[0:1], off
	v_lshl_add_u64 v[122:123], s[4:5], 0, v[14:15]
	v_readlane_b32 s4, v253, 3
	s_add_i32 s0, s22, 0x2080
	v_mov_b32_e32 v9, v137
	v_readlane_b32 s5, v253, 4
	v_mov_b32_e32 v11, v137
	v_mov_b32_e32 v13, v137
	v_mov_b32_e32 v14, v137
	v_lshlrev_b32_e32 v118, 3, v19
	v_mul_u32_u24_e32 v152, 0x90, v16
	v_mul_u32_u24_e32 v153, 0x90, v17
	v_lshl_add_u32 v154, v19, 4, s24
	v_lshl_add_u64 v[124:125], s[4:5], 0, v[8:9]
	v_lshl_add_u64 v[126:127], s[2:3], 0, v[8:9]
	v_lshl_add_u64 v[128:129], s[4:5], 0, v[10:11]
	v_lshl_add_u64 v[130:131], s[2:3], 0, v[10:11]
	v_lshl_add_u64 v[132:133], s[4:5], 0, v[12:13]
	v_lshl_add_u64 v[134:135], s[2:3], 0, v[12:13]
	v_mul_u32_u24_e32 v155, 0xd0, v18
	v_mul_u32_u24_e32 v142, 0x90, v18
	v_add_u32_sdwa v156, s0, v22 dst_sel:DWORD dst_unused:UNUSED_PAD src0_sel:DWORD src1_sel:WORD_1
	v_add_u32_sdwa v157, s0, v21 dst_sel:DWORD dst_unused:UNUSED_PAD src0_sel:DWORD src1_sel:WORD_1
	v_add_u32_e32 v158, s0, v20
	v_mov_b32_e32 v0, v137
	v_mov_b32_e32 v1, v137
	v_mov_b32_e32 v2, v137
	v_mov_b32_e32 v3, v137
	v_mov_b32_e32 v4, v137
	v_mov_b32_e32 v5, v137
	v_mov_b32_e32 v6, v137
	v_mov_b32_e32 v7, v137
	v_mov_b32_e32 v8, v137
	v_mov_b32_e32 v10, v137
	v_mov_b32_e32 v12, v137
	v_mov_b64_e32 v[30:31], v[14:15]
	v_add_u32_e32 v143, s24, v118
	s_mov_b32 s1, 0
	v_mov_b32_e32 v151, 0xf149f2ca
	v_mov_b32_e32 v119, 0
	v_mov_b64_e32 v[28:29], v[12:13]
	v_mov_b64_e32 v[26:27], v[10:11]
	v_mov_b64_e32 v[24:25], v[8:9]
	v_mov_b64_e32 v[22:23], v[6:7]
	v_mov_b64_e32 v[20:21], v[4:5]
	v_mov_b64_e32 v[18:19], v[2:3]
	v_mov_b64_e32 v[16:17], v[0:1]
	s_mov_b32 s3, 0
	s_movk_i32 s4, 0xff80
	s_mov_b32 s5, -1
	v_mov_b32_e32 v238, 0x1000
	v_mov_b32_e32 v239, 0x10000
	v_add_u32_e32 v32, s1, v158
	v_ashrrev_i32_e32 v33, 31, v32
	v_lshlrev_b64 v[34:35], 10, v[32:33]
	v_lshlrev_b64 v[32:33], 6, v[32:33]
	v_lshl_add_u64 v[32:33], v[124:125], 0, v[32:33]
	v_lshl_add_u64 v[34:35], v[126:127], 0, v[34:35]
	v_lshl_add_u64 v[32:33], v[32:33], 0, s[4:5]
	v_cndmask_b32_e64 v241, v33, v35, s[40:41]
	v_cndmask_b32_e64 v240, v32, v34, s[40:41]
	v_add_u32_e32 v32, s1, v157
	v_ashrrev_i32_e32 v33, 31, v32
	v_lshlrev_b64 v[34:35], 10, v[32:33]
	v_lshlrev_b64 v[32:33], 6, v[32:33]
	v_lshl_add_u64 v[32:33], v[128:129], 0, v[32:33]
	v_lshl_add_u64 v[34:35], v[130:131], 0, v[34:35]
	v_lshl_add_u64 v[32:33], v[32:33], 0, s[4:5]
	v_cndmask_b32_e64 v243, v33, v35, s[42:43]
	v_cndmask_b32_e64 v242, v32, v34, s[42:43]
	v_add_u32_e32 v32, s1, v156
	v_ashrrev_i32_e32 v33, 31, v32
	v_lshlrev_b64 v[34:35], 10, v[32:33]
	v_lshlrev_b64 v[32:33], 6, v[32:33]
	v_lshl_add_u64 v[32:33], v[132:133], 0, v[32:33]
	v_lshl_add_u64 v[34:35], v[134:135], 0, v[34:35]
	v_lshl_add_u64 v[32:33], v[32:33], 0, s[4:5]
	v_cndmask_b32_e64 v245, v33, v35, s[44:45]
	v_cndmask_b32_e64 v244, v32, v34, s[44:45]
	s_add_i32 s22, s0, s1
	s_ashr_i32 s23, s22, 31
	v_lshl_add_u64 v[32:33], s[22:23], 1, v[122:123]
	v_lshl_add_u64 v[246:247], v[32:33], 0, v[136:137]
	v_mov_b32_e32 v121, v137
	v_lshl_add_u64 v[248:249], v[32:33], 0, v[120:121]
	v_mov_b32_e32 v120, 0
	v_mov_b32_e32 v121, 0
	v_mov_b32_e32 v122, 0
	v_mov_b32_e32 v123, 0
	v_mov_b32_e32 v124, 0
	v_mov_b32_e32 v125, 0
	v_mov_b32_e32 v126, 0
	v_mov_b32_e32 v127, 0
	v_mov_b32_e32 v128, 0
	v_mov_b32_e32 v129, 0
	v_mov_b32_e32 v130, 0
	v_mov_b32_e32 v131, 0
	v_mov_b32_e32 v132, 0
	v_mov_b32_e32 v133, 0
	v_mov_b32_e32 v134, 0
	v_mov_b32_e32 v135, 0
	s_waitcnt lgkmcnt(0)
	s_barrier
	v_readfirstlane_b32 s22, v139
	s_bitcmp1_b32 s22, 8
	s_cbranch_scc0 .Lsa_vb0
	s_barrier
	s_branch .Lsa_no_e1
.Lsa_vb0:
	s_setprio 1
